# GEMM K-loops: drop the redundant priority 0/1 toggle between the two 16-MFMA halves of each phase
# baseline (speedup 1.0000x reference)
.LBB0_673:
	s_add_u32 s20, s18, 0xfff80080
	s_addc_u32 s21, s19, -1
	s_add_i32 s51, 0, 0x10000
	s_cmp_eq_u32 s49, 28
	s_cselect_b32 s23, s11, s21
	s_cselect_b32 s22, s46, s20
	v_add_u32_e32 v143, s51, v140
	s_cselect_b32 s21, s9, s48
	s_cselect_b32 s20, s47, s50
	s_add_i32 s56, 0, 0x14000
	ds_read_b128 v[144:147], v143
	ds_read_b128 v[148:151], v143 offset:1024
	ds_read_b128 v[152:155], v143 offset:2048
	ds_read_b128 v[156:159], v143 offset:3072
	v_add_u32_e32 v143, s56, v140
	ds_read_b128 v[160:163], v143
	ds_read_b128 v[164:167], v143 offset:1024
	ds_read_b128 v[168:171], v143 offset:2048
	ds_read_b128 v[172:175], v143 offset:3072
	v_lshl_add_u64 v[210:211], s[18:19], 0, v[134:135]
	s_add_i32 m0, s13, 0xc000
	ds_read_b128 v[178:181], v142
	ds_read_b128 v[182:185], v142 offset:1024
	ds_read_b128 v[186:189], v142 offset:2048
	ds_read_b128 v[190:193], v142 offset:3072
	ds_read_b128 v[194:197], v142 offset:4096
	ds_read_b128 v[198:201], v142 offset:5120
	ds_read_b128 v[202:205], v142 offset:6144
	ds_read_b128 v[206:209], v142 offset:7168
	global_load_lds_dwordx4 v[210:211], off
	v_lshl_add_u64 v[210:211], s[18:19], 0, v[136:137]
	s_add_i32 m0, s13, 0xe000
	s_nop 0
	global_load_lds_dwordx4 v[210:211], off
	s_waitcnt vmcnt(8)
	s_waitcnt lgkmcnt(0)
	s_barrier
	s_setprio 1
	s_waitcnt lgkmcnt(0)
	v_mfma_f32_16x16x32_bf16 v[124:127], v[144:147], v[178:181], v[124:127]
	v_mfma_f32_16x16x32_bf16 v[120:123], v[152:155], v[178:181], v[120:123]
	v_mfma_f32_16x16x32_bf16 v[116:119], v[144:147], v[186:189], v[116:119]
	v_mfma_f32_16x16x32_bf16 v[112:115], v[152:155], v[186:189], v[112:115]
	v_mfma_f32_16x16x32_bf16 v[100:103], v[144:147], v[194:197], v[100:103]
	v_mfma_f32_16x16x32_bf16 v[96:99], v[152:155], v[194:197], v[96:99]
	v_mfma_f32_16x16x32_bf16 v[84:87], v[144:147], v[202:205], v[84:87]
	v_mfma_f32_16x16x32_bf16 v[80:83], v[152:155], v[202:205], v[80:83]
	v_mfma_f32_16x16x32_bf16 v[124:127], v[148:151], v[182:185], v[124:127]
	v_mfma_f32_16x16x32_bf16 v[120:123], v[156:159], v[182:185], v[120:123]
	v_mfma_f32_16x16x32_bf16 v[116:119], v[148:151], v[190:193], v[116:119]
	v_mfma_f32_16x16x32_bf16 v[112:115], v[156:159], v[190:193], v[112:115]
	v_mfma_f32_16x16x32_bf16 v[100:103], v[148:151], v[198:201], v[100:103]
	v_mfma_f32_16x16x32_bf16 v[96:99], v[156:159], v[198:201], v[96:99]
	v_mfma_f32_16x16x32_bf16 v[84:87], v[148:151], v[206:209], v[84:87]
	v_mfma_f32_16x16x32_bf16 v[80:83], v[156:159], v[206:209], v[80:83]
	v_mfma_f32_16x16x32_bf16 v[108:111], v[160:163], v[178:181], v[108:111]
	v_mfma_f32_16x16x32_bf16 v[104:107], v[168:171], v[178:181], v[104:107]
	v_mfma_f32_16x16x32_bf16 v[92:95], v[160:163], v[186:189], v[92:95]
	v_mfma_f32_16x16x32_bf16 v[88:91], v[168:171], v[186:189], v[88:91]
	v_mfma_f32_16x16x32_bf16 v[76:79], v[160:163], v[194:197], v[76:79]
	v_mfma_f32_16x16x32_bf16 v[72:75], v[168:171], v[194:197], v[72:75]
	v_mfma_f32_16x16x32_bf16 v[68:71], v[160:163], v[202:205], v[68:71]
	v_mfma_f32_16x16x32_bf16 v[64:67], v[168:171], v[202:205], v[64:67]
	v_mfma_f32_16x16x32_bf16 v[108:111], v[164:167], v[182:185], v[108:111]
	v_mfma_f32_16x16x32_bf16 v[104:107], v[172:175], v[182:185], v[104:107]
	v_mfma_f32_16x16x32_bf16 v[92:95], v[164:167], v[190:193], v[92:95]
	v_mfma_f32_16x16x32_bf16 v[88:91], v[172:175], v[190:193], v[88:91]
	v_mfma_f32_16x16x32_bf16 v[76:79], v[164:167], v[198:201], v[76:79]
	v_mfma_f32_16x16x32_bf16 v[72:75], v[172:175], v[198:201], v[72:75]
	v_mfma_f32_16x16x32_bf16 v[68:71], v[164:167], v[206:209], v[68:71]
	v_mfma_f32_16x16x32_bf16 v[64:67], v[172:175], v[206:209], v[64:67]
	s_setprio 0
	s_barrier
	s_add_i32 s51, s51, s28
	v_lshl_add_u64 v[210:211], s[20:21], 0, v[176:177]
	s_mov_b32 m0, s51
	ds_read_b128 v[178:181], v142 offset:16384
	ds_read_b128 v[182:185], v142 offset:17408
	ds_read_b128 v[186:189], v142 offset:18432
	ds_read_b128 v[190:193], v142 offset:19456
	ds_read_b128 v[194:197], v142 offset:20480
	ds_read_b128 v[198:201], v142 offset:21504
	ds_read_b128 v[202:205], v142 offset:22528
	ds_read_b128 v[206:209], v142 offset:23552
	global_load_lds_dwordx4 v[210:211], off
	s_add_i32 m0, s51, 0x2000
	s_add_u32 s54, s20, 0x80000
	v_lshl_add_u64 v[212:213], s[20:21], 0, v[128:129]
	s_addc_u32 s55, s21, 0
	s_add_i32 s51, s56, s28
	global_load_lds_dwordx4 v[212:213], off
	v_lshl_add_u64 v[220:221], s[54:55], 0, v[176:177]
	s_mov_b32 m0, s51
	v_lshl_add_u64 v[222:223], s[22:23], 0, v[130:131]
	global_load_lds_dwordx4 v[220:221], off
	v_lshl_add_u64 v[220:221], s[54:55], 0, v[128:129]
	s_add_i32 m0, s51, 0x2000
	s_nop 0
	global_load_lds_dwordx4 v[220:221], off
	v_lshl_add_u64 v[220:221], s[22:23], 0, v[132:133]
	s_mov_b32 m0, s13
	s_nop 0
	global_load_lds_dwordx4 v[220:221], off
	s_mov_b32 m0, s30
	s_nop 0
	global_load_lds_dwordx4 v[222:223], off
	s_waitcnt vmcnt(8)
	s_waitcnt lgkmcnt(0)
	s_barrier
	s_setprio 1
	s_waitcnt lgkmcnt(0)
	v_mfma_f32_16x16x32_bf16 v[60:63], v[144:147], v[178:181], v[60:63]
	v_mfma_f32_16x16x32_bf16 v[56:59], v[152:155], v[178:181], v[56:59]
	v_mfma_f32_16x16x32_bf16 v[52:55], v[144:147], v[186:189], v[52:55]
	v_mfma_f32_16x16x32_bf16 v[48:51], v[152:155], v[186:189], v[48:51]
	v_mfma_f32_16x16x32_bf16 v[36:39], v[144:147], v[194:197], v[36:39]
	v_mfma_f32_16x16x32_bf16 v[32:35], v[152:155], v[194:197], v[32:35]
	v_mfma_f32_16x16x32_bf16 v[20:23], v[144:147], v[202:205], v[20:23]
	v_mfma_f32_16x16x32_bf16 v[16:19], v[152:155], v[202:205], v[16:19]
	v_mfma_f32_16x16x32_bf16 v[60:63], v[148:151], v[182:185], v[60:63]
	v_mfma_f32_16x16x32_bf16 v[56:59], v[156:159], v[182:185], v[56:59]
	v_mfma_f32_16x16x32_bf16 v[52:55], v[148:151], v[190:193], v[52:55]
	v_mfma_f32_16x16x32_bf16 v[48:51], v[156:159], v[190:193], v[48:51]
	v_mfma_f32_16x16x32_bf16 v[36:39], v[148:151], v[198:201], v[36:39]
	v_mfma_f32_16x16x32_bf16 v[32:35], v[156:159], v[198:201], v[32:35]
	v_mfma_f32_16x16x32_bf16 v[20:23], v[148:151], v[206:209], v[20:23]
	v_mfma_f32_16x16x32_bf16 v[16:19], v[156:159], v[206:209], v[16:19]
	v_mfma_f32_16x16x32_bf16 v[44:47], v[160:163], v[178:181], v[44:47]
	v_mfma_f32_16x16x32_bf16 v[40:43], v[168:171], v[178:181], v[40:43]
	v_mfma_f32_16x16x32_bf16 v[28:31], v[160:163], v[186:189], v[28:31]
	v_mfma_f32_16x16x32_bf16 v[24:27], v[168:171], v[186:189], v[24:27]
	v_mfma_f32_16x16x32_bf16 v[12:15], v[160:163], v[194:197], v[12:15]
	v_mfma_f32_16x16x32_bf16 v[8:11], v[168:171], v[194:197], v[8:11]
	v_mfma_f32_16x16x32_bf16 v[4:7], v[160:163], v[202:205], v[4:7]
	v_mfma_f32_16x16x32_bf16 v[0:3], v[168:171], v[202:205], v[0:3]
	v_mfma_f32_16x16x32_bf16 v[44:47], v[164:167], v[182:185], v[44:47]
	v_mfma_f32_16x16x32_bf16 v[40:43], v[172:175], v[182:185], v[40:43]
	v_mfma_f32_16x16x32_bf16 v[28:31], v[164:167], v[190:193], v[28:31]
	v_mfma_f32_16x16x32_bf16 v[24:27], v[172:175], v[190:193], v[24:27]
	v_mfma_f32_16x16x32_bf16 v[12:15], v[164:167], v[198:201], v[12:15]
	v_mfma_f32_16x16x32_bf16 v[8:11], v[172:175], v[198:201], v[8:11]
	v_mfma_f32_16x16x32_bf16 v[4:7], v[164:167], v[206:209], v[4:7]
	v_mfma_f32_16x16x32_bf16 v[0:3], v[172:175], v[206:209], v[0:3]
	s_setprio 0
	s_barrier
	s_add_i32 s51, 0, 0x18000
	v_add_u32_e32 v143, s51, v140
	s_add_i32 s54, 0, 0x1c000
	ds_read_b128 v[144:147], v143
	ds_read_b128 v[148:151], v143 offset:1024
	ds_read_b128 v[152:155], v143 offset:2048
	ds_read_b128 v[156:159], v143 offset:3072
	v_add_u32_e32 v143, s54, v140
	ds_read_b128 v[160:163], v143
	ds_read_b128 v[164:167], v143 offset:1024
	ds_read_b128 v[168:171], v143 offset:2048
	ds_read_b128 v[172:175], v143 offset:3072
	s_add_u32 s22, s22, 0x80000
	s_addc_u32 s23, s23, 0
	s_mov_b32 m0, s31
	v_lshl_add_u64 v[232:233], s[22:23], 0, v[132:133]
	ds_read_b128 v[178:181], v142 offset:32768
	ds_read_b128 v[182:185], v142 offset:33792
	ds_read_b128 v[186:189], v142 offset:34816
	ds_read_b128 v[190:193], v142 offset:35840
	ds_read_b128 v[194:197], v142 offset:36864
	ds_read_b128 v[198:201], v142 offset:37888
	ds_read_b128 v[202:205], v142 offset:38912
	ds_read_b128 v[206:209], v142 offset:39936
	global_load_lds_dwordx4 v[232:233], off
	v_lshl_add_u64 v[232:233], s[22:23], 0, v[130:131]
	s_mov_b32 m0, s33
	s_nop 0
	global_load_lds_dwordx4 v[232:233], off
	s_waitcnt vmcnt(8)
	s_waitcnt lgkmcnt(0)
	s_barrier
	s_setprio 1
	s_waitcnt lgkmcnt(0)
	v_mfma_f32_16x16x32_bf16 v[124:127], v[144:147], v[178:181], v[124:127]
	v_mfma_f32_16x16x32_bf16 v[120:123], v[152:155], v[178:181], v[120:123]
	v_mfma_f32_16x16x32_bf16 v[116:119], v[144:147], v[186:189], v[116:119]
	v_mfma_f32_16x16x32_bf16 v[112:115], v[152:155], v[186:189], v[112:115]
	v_mfma_f32_16x16x32_bf16 v[100:103], v[144:147], v[194:197], v[100:103]
	v_mfma_f32_16x16x32_bf16 v[96:99], v[152:155], v[194:197], v[96:99]
	v_mfma_f32_16x16x32_bf16 v[84:87], v[144:147], v[202:205], v[84:87]
	v_mfma_f32_16x16x32_bf16 v[80:83], v[152:155], v[202:205], v[80:83]
	v_mfma_f32_16x16x32_bf16 v[124:127], v[148:151], v[182:185], v[124:127]
	v_mfma_f32_16x16x32_bf16 v[120:123], v[156:159], v[182:185], v[120:123]
	v_mfma_f32_16x16x32_bf16 v[116:119], v[148:151], v[190:193], v[116:119]
	v_mfma_f32_16x16x32_bf16 v[112:115], v[156:159], v[190:193], v[112:115]
	v_mfma_f32_16x16x32_bf16 v[100:103], v[148:151], v[198:201], v[100:103]
	v_mfma_f32_16x16x32_bf16 v[96:99], v[156:159], v[198:201], v[96:99]
	v_mfma_f32_16x16x32_bf16 v[84:87], v[148:151], v[206:209], v[84:87]
	v_mfma_f32_16x16x32_bf16 v[80:83], v[156:159], v[206:209], v[80:83]
	v_mfma_f32_16x16x32_bf16 v[108:111], v[160:163], v[178:181], v[108:111]
	v_mfma_f32_16x16x32_bf16 v[104:107], v[168:171], v[178:181], v[104:107]
	v_mfma_f32_16x16x32_bf16 v[92:95], v[160:163], v[186:189], v[92:95]
	v_mfma_f32_16x16x32_bf16 v[88:91], v[168:171], v[186:189], v[88:91]
	v_mfma_f32_16x16x32_bf16 v[76:79], v[160:163], v[194:197], v[76:79]
	v_mfma_f32_16x16x32_bf16 v[72:75], v[168:171], v[194:197], v[72:75]
	v_mfma_f32_16x16x32_bf16 v[68:71], v[160:163], v[202:205], v[68:71]
	v_mfma_f32_16x16x32_bf16 v[64:67], v[168:171], v[202:205], v[64:67]
	v_mfma_f32_16x16x32_bf16 v[108:111], v[164:167], v[182:185], v[108:111]
	v_mfma_f32_16x16x32_bf16 v[104:107], v[172:175], v[182:185], v[104:107]
	v_mfma_f32_16x16x32_bf16 v[92:95], v[164:167], v[190:193], v[92:95]
	v_mfma_f32_16x16x32_bf16 v[88:91], v[172:175], v[190:193], v[88:91]
	v_mfma_f32_16x16x32_bf16 v[76:79], v[164:167], v[198:201], v[76:79]
	v_mfma_f32_16x16x32_bf16 v[72:75], v[172:175], v[198:201], v[72:75]
	v_mfma_f32_16x16x32_bf16 v[68:71], v[164:167], v[206:209], v[68:71]
	v_mfma_f32_16x16x32_bf16 v[64:67], v[172:175], v[206:209], v[64:67]
	s_setprio 0
	s_barrier
	s_add_i32 s22, s51, s28
	v_lshl_add_u64 v[210:211], v[210:211], 0, s[40:41]
	s_mov_b32 m0, s22
	ds_read_b128 v[178:181], v142 offset:49152
	ds_read_b128 v[182:185], v142 offset:50176
	ds_read_b128 v[186:189], v142 offset:51200
	ds_read_b128 v[190:193], v142 offset:52224
	ds_read_b128 v[194:197], v142 offset:53248
	ds_read_b128 v[198:201], v142 offset:54272
	ds_read_b128 v[202:205], v142 offset:55296
	ds_read_b128 v[206:209], v142 offset:56320
	global_load_lds_dwordx4 v[210:211], off
	s_add_i32 m0, s22, 0x2000
	s_add_u32 s20, s20, 0x80080
	v_lshl_add_u64 v[210:211], v[212:213], 0, s[40:41]
	s_addc_u32 s21, s21, 0
	s_add_i32 s22, s54, s28
	global_load_lds_dwordx4 v[210:211], off
	v_lshl_add_u64 v[210:211], s[20:21], 0, v[176:177]
	s_mov_b32 m0, s22
	s_nop 0
	global_load_lds_dwordx4 v[210:211], off
	v_lshl_add_u64 v[210:211], s[20:21], 0, v[128:129]
	s_add_i32 m0, s22, 0x2000
	s_nop 0
	global_load_lds_dwordx4 v[210:211], off
	v_lshl_add_u64 v[210:211], v[220:221], 0, s[40:41]
	s_mov_b32 m0, s34
	s_nop 0
	global_load_lds_dwordx4 v[210:211], off
	v_lshl_add_u64 v[210:211], v[222:223], 0, s[40:41]
	s_mov_b32 m0, s35
	s_nop 0
	global_load_lds_dwordx4 v[210:211], off
	s_waitcnt vmcnt(8)
	s_waitcnt lgkmcnt(0)
	s_barrier
	s_setprio 1
	s_waitcnt lgkmcnt(0)
	v_mfma_f32_16x16x32_bf16 v[60:63], v[144:147], v[178:181], v[60:63]
	v_mfma_f32_16x16x32_bf16 v[56:59], v[152:155], v[178:181], v[56:59]
	v_mfma_f32_16x16x32_bf16 v[52:55], v[144:147], v[186:189], v[52:55]
	v_mfma_f32_16x16x32_bf16 v[48:51], v[152:155], v[186:189], v[48:51]
	v_mfma_f32_16x16x32_bf16 v[36:39], v[144:147], v[194:197], v[36:39]
	v_mfma_f32_16x16x32_bf16 v[32:35], v[152:155], v[194:197], v[32:35]
	v_mfma_f32_16x16x32_bf16 v[20:23], v[144:147], v[202:205], v[20:23]
	v_mfma_f32_16x16x32_bf16 v[16:19], v[152:155], v[202:205], v[16:19]
	v_mfma_f32_16x16x32_bf16 v[60:63], v[148:151], v[182:185], v[60:63]
	v_mfma_f32_16x16x32_bf16 v[56:59], v[156:159], v[182:185], v[56:59]
	v_mfma_f32_16x16x32_bf16 v[52:55], v[148:151], v[190:193], v[52:55]
	v_mfma_f32_16x16x32_bf16 v[48:51], v[156:159], v[190:193], v[48:51]
	v_mfma_f32_16x16x32_bf16 v[36:39], v[148:151], v[198:201], v[36:39]
	v_mfma_f32_16x16x32_bf16 v[32:35], v[156:159], v[198:201], v[32:35]
	v_mfma_f32_16x16x32_bf16 v[20:23], v[148:151], v[206:209], v[20:23]
	v_mfma_f32_16x16x32_bf16 v[16:19], v[156:159], v[206:209], v[16:19]
	v_mfma_f32_16x16x32_bf16 v[44:47], v[160:163], v[178:181], v[44:47]
	v_mfma_f32_16x16x32_bf16 v[40:43], v[168:171], v[178:181], v[40:43]
	v_mfma_f32_16x16x32_bf16 v[28:31], v[160:163], v[186:189], v[28:31]
	v_mfma_f32_16x16x32_bf16 v[24:27], v[168:171], v[186:189], v[24:27]
	v_mfma_f32_16x16x32_bf16 v[12:15], v[160:163], v[194:197], v[12:15]
	v_mfma_f32_16x16x32_bf16 v[8:11], v[168:171], v[194:197], v[8:11]
	v_mfma_f32_16x16x32_bf16 v[4:7], v[160:163], v[202:205], v[4:7]
	v_mfma_f32_16x16x32_bf16 v[0:3], v[168:171], v[202:205], v[0:3]
	v_mfma_f32_16x16x32_bf16 v[44:47], v[164:167], v[182:185], v[44:47]
	v_mfma_f32_16x16x32_bf16 v[40:43], v[172:175], v[182:185], v[40:43]
	v_mfma_f32_16x16x32_bf16 v[28:31], v[164:167], v[190:193], v[28:31]
	v_mfma_f32_16x16x32_bf16 v[24:27], v[172:175], v[190:193], v[24:27]
	v_mfma_f32_16x16x32_bf16 v[12:15], v[164:167], v[198:201], v[12:15]
	v_mfma_f32_16x16x32_bf16 v[8:11], v[172:175], v[198:201], v[8:11]
	v_mfma_f32_16x16x32_bf16 v[4:7], v[164:167], v[206:209], v[4:7]
	v_mfma_f32_16x16x32_bf16 v[0:3], v[172:175], v[206:209], v[0:3]
	s_setprio 0
	s_barrier
	s_add_i32 s49, s49, 2
	s_add_u32 s18, s18, 0x100
	s_addc_u32 s19, s19, 0
	s_add_u32 s50, s50, 0x100
	s_addc_u32 s48, s48, 0
	s_cmp_gt_u32 s49, 29
	s_cbranch_scc0 .LBB0_673
	s_and_b64 vcc, exec, s[6:7]
	s_cbranch_vccz .LBB0_676
	s_barrier

.LBB0_1261:
	s_add_i32 s97, s26, 2
	s_add_u32 s24, s22, 0x100
	s_addc_u32 s25, s23, 0
	s_add_i32 s88, 0, 0x10000
	s_cmp_eq_u32 s48, s26
	s_cselect_b32 s29, s11, s25
	s_cselect_b32 s28, vcc_lo, s24
	s_cselect_b32 s27, s9, s96
	s_cselect_b32 s26, vcc_hi, s49
	s_add_i32 s89, 0, 0x14000
	v_add_u32_e32 v140, s88, v160
	v_add_u32_e32 v166, s89, v160
	ds_read_b128 v[128:131], v140
	ds_read_b128 v[132:135], v140 offset:1024
	ds_read_b128 v[136:139], v140 offset:2048
	ds_read_b128 v[140:143], v140 offset:3072
	ds_read_b128 v[150:153], v166
	ds_read_b128 v[154:157], v166 offset:1024
	ds_read_b128 v[162:165], v166 offset:2048
	ds_read_b128 v[166:169], v166 offset:3072
	v_lshl_add_u64 v[174:175], s[22:23], 0, v[146:147]
	s_add_i32 m0, s35, 0xc000
	ds_read_b128 v[170:173], v161
	ds_read_b128 v[178:181], v161 offset:1024
	ds_read_b128 v[182:185], v161 offset:2048
	ds_read_b128 v[186:189], v161 offset:3072
	ds_read_b128 v[190:193], v161 offset:4096
	ds_read_b128 v[194:197], v161 offset:5120
	ds_read_b128 v[198:201], v161 offset:6144
	ds_read_b128 v[202:205], v161 offset:7168
	global_load_lds_dwordx4 v[174:175], off
	v_lshl_add_u64 v[174:175], s[22:23], 0, v[148:149]
	s_add_i32 m0, s35, 0xe000
	s_nop 0
	global_load_lds_dwordx4 v[174:175], off
	s_waitcnt vmcnt(8)
	s_waitcnt lgkmcnt(0)
	s_barrier
	s_setprio 1
	s_waitcnt lgkmcnt(0)
	v_mfma_f32_16x16x32_bf16 v[124:127], v[128:131], v[170:173], v[124:127]
	v_mfma_f32_16x16x32_bf16 v[120:123], v[136:139], v[170:173], v[120:123]
	v_mfma_f32_16x16x32_bf16 v[112:115], v[128:131], v[182:185], v[112:115]
	v_mfma_f32_16x16x32_bf16 v[108:111], v[136:139], v[182:185], v[108:111]
	v_mfma_f32_16x16x32_bf16 v[100:103], v[128:131], v[190:193], v[100:103]
	v_mfma_f32_16x16x32_bf16 v[92:95], v[136:139], v[190:193], v[92:95]
	v_mfma_f32_16x16x32_bf16 v[84:87], v[128:131], v[198:201], v[84:87]
	v_mfma_f32_16x16x32_bf16 v[76:79], v[136:139], v[198:201], v[76:79]
	v_mfma_f32_16x16x32_bf16 v[124:127], v[132:135], v[178:181], v[124:127]
	v_mfma_f32_16x16x32_bf16 v[120:123], v[140:143], v[178:181], v[120:123]
	v_mfma_f32_16x16x32_bf16 v[112:115], v[132:135], v[186:189], v[112:115]
	v_mfma_f32_16x16x32_bf16 v[108:111], v[140:143], v[186:189], v[108:111]
	v_mfma_f32_16x16x32_bf16 v[100:103], v[132:135], v[194:197], v[100:103]
	v_mfma_f32_16x16x32_bf16 v[92:95], v[140:143], v[194:197], v[92:95]
	v_mfma_f32_16x16x32_bf16 v[84:87], v[132:135], v[202:205], v[84:87]
	v_mfma_f32_16x16x32_bf16 v[76:79], v[140:143], v[202:205], v[76:79]
	v_mfma_f32_16x16x32_bf16 v[116:119], v[150:153], v[170:173], v[116:119]
	v_mfma_f32_16x16x32_bf16 v[104:107], v[162:165], v[170:173], v[104:107]
	v_mfma_f32_16x16x32_bf16 v[96:99], v[150:153], v[182:185], v[96:99]
	v_mfma_f32_16x16x32_bf16 v[88:91], v[162:165], v[182:185], v[88:91]
	v_mfma_f32_16x16x32_bf16 v[80:83], v[150:153], v[190:193], v[80:83]
	v_mfma_f32_16x16x32_bf16 v[72:75], v[162:165], v[190:193], v[72:75]
	v_mfma_f32_16x16x32_bf16 v[68:71], v[150:153], v[198:201], v[68:71]
	v_mfma_f32_16x16x32_bf16 v[64:67], v[162:165], v[198:201], v[64:67]
	v_mfma_f32_16x16x32_bf16 v[116:119], v[154:157], v[178:181], v[116:119]
	v_mfma_f32_16x16x32_bf16 v[104:107], v[166:169], v[178:181], v[104:107]
	v_mfma_f32_16x16x32_bf16 v[96:99], v[154:157], v[186:189], v[96:99]
	v_mfma_f32_16x16x32_bf16 v[88:91], v[166:169], v[186:189], v[88:91]
	v_mfma_f32_16x16x32_bf16 v[80:83], v[154:157], v[194:197], v[80:83]
	v_mfma_f32_16x16x32_bf16 v[72:75], v[166:169], v[194:197], v[72:75]
	v_mfma_f32_16x16x32_bf16 v[68:71], v[154:157], v[202:205], v[68:71]
	v_mfma_f32_16x16x32_bf16 v[64:67], v[166:169], v[202:205], v[64:67]
	s_setprio 0
	s_barrier
	s_add_i32 s22, s88, s34
	v_lshl_add_u64 v[174:175], s[26:27], 0, v[176:177]
	s_mov_b32 m0, s22
	ds_read_b128 v[170:173], v161 offset:16384
	ds_read_b128 v[178:181], v161 offset:17408
	ds_read_b128 v[182:185], v161 offset:18432
	ds_read_b128 v[186:189], v161 offset:19456
	ds_read_b128 v[190:193], v161 offset:20480
	ds_read_b128 v[194:197], v161 offset:21504
	ds_read_b128 v[198:201], v161 offset:22528
	ds_read_b128 v[202:205], v161 offset:23552
	global_load_lds_dwordx4 v[174:175], off
	s_add_i32 m0, s22, 0x2000
	s_add_u32 s22, s26, 0x80000
	v_lshl_add_u64 v[206:207], s[26:27], 0, v[144:145]
	s_addc_u32 s23, s27, 0
	s_add_i32 s88, s89, s34
	global_load_lds_dwordx4 v[206:207], off
	v_lshl_add_u64 v[208:209], s[22:23], 0, v[176:177]
	s_mov_b32 m0, s88
	v_lshl_add_u64 v[210:211], s[28:29], 0, v[144:145]
	global_load_lds_dwordx4 v[208:209], off
	v_lshl_add_u64 v[208:209], s[22:23], 0, v[144:145]
	s_add_i32 m0, s88, 0x2000
	s_nop 0
	global_load_lds_dwordx4 v[208:209], off
	v_lshl_add_u64 v[208:209], s[28:29], 0, v[176:177]
	s_mov_b32 m0, s35
	s_nop 0
	global_load_lds_dwordx4 v[208:209], off
	s_mov_b32 m0, s36
	s_nop 0
	global_load_lds_dwordx4 v[210:211], off
	s_waitcnt vmcnt(8)
	s_waitcnt lgkmcnt(0)
	s_barrier
	s_setprio 1
	s_waitcnt lgkmcnt(0)
	v_mfma_f32_16x16x32_bf16 v[60:63], v[128:131], v[170:173], v[60:63]
	v_mfma_f32_16x16x32_bf16 v[56:59], v[136:139], v[170:173], v[56:59]
	v_mfma_f32_16x16x32_bf16 v[52:55], v[128:131], v[182:185], v[52:55]
	v_mfma_f32_16x16x32_bf16 v[44:47], v[136:139], v[182:185], v[44:47]
	v_mfma_f32_16x16x32_bf16 v[36:39], v[128:131], v[190:193], v[36:39]
	v_mfma_f32_16x16x32_bf16 v[28:31], v[136:139], v[190:193], v[28:31]
	v_mfma_f32_16x16x32_bf16 v[16:19], v[128:131], v[198:201], v[16:19]
	v_mfma_f32_16x16x32_bf16 v[8:11], v[136:139], v[198:201], v[8:11]
	v_mfma_f32_16x16x32_bf16 v[60:63], v[132:135], v[178:181], v[60:63]
	v_mfma_f32_16x16x32_bf16 v[56:59], v[140:143], v[178:181], v[56:59]
	v_mfma_f32_16x16x32_bf16 v[52:55], v[132:135], v[186:189], v[52:55]
	v_mfma_f32_16x16x32_bf16 v[44:47], v[140:143], v[186:189], v[44:47]
	v_mfma_f32_16x16x32_bf16 v[36:39], v[132:135], v[194:197], v[36:39]
	v_mfma_f32_16x16x32_bf16 v[28:31], v[140:143], v[194:197], v[28:31]
	v_mfma_f32_16x16x32_bf16 v[16:19], v[132:135], v[202:205], v[16:19]
	v_mfma_f32_16x16x32_bf16 v[8:11], v[140:143], v[202:205], v[8:11]
	v_mfma_f32_16x16x32_bf16 v[48:51], v[150:153], v[170:173], v[48:51]
	v_mfma_f32_16x16x32_bf16 v[40:43], v[162:165], v[170:173], v[40:43]
	v_mfma_f32_16x16x32_bf16 v[32:35], v[150:153], v[182:185], v[32:35]
	v_mfma_f32_16x16x32_bf16 v[24:27], v[162:165], v[182:185], v[24:27]
	v_mfma_f32_16x16x32_bf16 v[20:23], v[150:153], v[190:193], v[20:23]
	v_mfma_f32_16x16x32_bf16 v[12:15], v[162:165], v[190:193], v[12:15]
	v_mfma_f32_16x16x32_bf16 v[4:7], v[150:153], v[198:201], v[4:7]
	v_mfma_f32_16x16x32_bf16 v[0:3], v[162:165], v[198:201], v[0:3]
	v_mfma_f32_16x16x32_bf16 v[48:51], v[154:157], v[178:181], v[48:51]
	v_mfma_f32_16x16x32_bf16 v[40:43], v[166:169], v[178:181], v[40:43]
	v_mfma_f32_16x16x32_bf16 v[32:35], v[154:157], v[186:189], v[32:35]
	v_mfma_f32_16x16x32_bf16 v[24:27], v[166:169], v[186:189], v[24:27]
	v_mfma_f32_16x16x32_bf16 v[20:23], v[154:157], v[194:197], v[20:23]
	v_mfma_f32_16x16x32_bf16 v[12:15], v[166:169], v[194:197], v[12:15]
	v_mfma_f32_16x16x32_bf16 v[4:7], v[154:157], v[202:205], v[4:7]
	v_mfma_f32_16x16x32_bf16 v[0:3], v[166:169], v[202:205], v[0:3]
	s_setprio 0
	s_barrier
	s_add_i32 s88, 0, 0x18000
	s_add_i32 s89, 0, 0x1c000
	v_add_u32_e32 v140, s88, v160
	v_add_u32_e32 v166, s89, v160
	ds_read_b128 v[128:131], v140
	ds_read_b128 v[132:135], v140 offset:1024
	ds_read_b128 v[136:139], v140 offset:2048
	ds_read_b128 v[140:143], v140 offset:3072
	ds_read_b128 v[150:153], v166
	ds_read_b128 v[154:157], v166 offset:1024
	ds_read_b128 v[162:165], v166 offset:2048
	ds_read_b128 v[166:169], v166 offset:3072
	s_add_u32 s22, s28, 0x80000
	s_addc_u32 s23, s29, 0
	s_mov_b32 m0, s37
	v_lshl_add_u64 v[212:213], s[22:23], 0, v[176:177]
	ds_read_b128 v[170:173], v161 offset:32768
	ds_read_b128 v[178:181], v161 offset:33792
	ds_read_b128 v[182:185], v161 offset:34816
	ds_read_b128 v[186:189], v161 offset:35840
	ds_read_b128 v[190:193], v161 offset:36864
	ds_read_b128 v[194:197], v161 offset:37888
	ds_read_b128 v[198:201], v161 offset:38912
	ds_read_b128 v[202:205], v161 offset:39936
	global_load_lds_dwordx4 v[212:213], off
	v_lshl_add_u64 v[212:213], s[22:23], 0, v[144:145]
	s_mov_b32 m0, s72
	s_nop 0
	global_load_lds_dwordx4 v[212:213], off
	s_waitcnt vmcnt(8)
	s_waitcnt lgkmcnt(0)
	s_barrier
	s_setprio 1
	s_waitcnt lgkmcnt(0)
	v_mfma_f32_16x16x32_bf16 v[124:127], v[128:131], v[170:173], v[124:127]
	v_mfma_f32_16x16x32_bf16 v[120:123], v[136:139], v[170:173], v[120:123]
	v_mfma_f32_16x16x32_bf16 v[112:115], v[128:131], v[182:185], v[112:115]
	v_mfma_f32_16x16x32_bf16 v[108:111], v[136:139], v[182:185], v[108:111]
	v_mfma_f32_16x16x32_bf16 v[100:103], v[128:131], v[190:193], v[100:103]
	v_mfma_f32_16x16x32_bf16 v[92:95], v[136:139], v[190:193], v[92:95]
	v_mfma_f32_16x16x32_bf16 v[84:87], v[128:131], v[198:201], v[84:87]
	v_mfma_f32_16x16x32_bf16 v[76:79], v[136:139], v[198:201], v[76:79]
	v_mfma_f32_16x16x32_bf16 v[124:127], v[132:135], v[178:181], v[124:127]
	v_mfma_f32_16x16x32_bf16 v[120:123], v[140:143], v[178:181], v[120:123]
	v_mfma_f32_16x16x32_bf16 v[112:115], v[132:135], v[186:189], v[112:115]
	v_mfma_f32_16x16x32_bf16 v[108:111], v[140:143], v[186:189], v[108:111]
	v_mfma_f32_16x16x32_bf16 v[100:103], v[132:135], v[194:197], v[100:103]
	v_mfma_f32_16x16x32_bf16 v[92:95], v[140:143], v[194:197], v[92:95]
	v_mfma_f32_16x16x32_bf16 v[84:87], v[132:135], v[202:205], v[84:87]
	v_mfma_f32_16x16x32_bf16 v[76:79], v[140:143], v[202:205], v[76:79]
	v_mfma_f32_16x16x32_bf16 v[116:119], v[150:153], v[170:173], v[116:119]
	v_mfma_f32_16x16x32_bf16 v[104:107], v[162:165], v[170:173], v[104:107]
	v_mfma_f32_16x16x32_bf16 v[96:99], v[150:153], v[182:185], v[96:99]
	v_mfma_f32_16x16x32_bf16 v[88:91], v[162:165], v[182:185], v[88:91]
	v_mfma_f32_16x16x32_bf16 v[80:83], v[150:153], v[190:193], v[80:83]
	v_mfma_f32_16x16x32_bf16 v[72:75], v[162:165], v[190:193], v[72:75]
	v_mfma_f32_16x16x32_bf16 v[68:71], v[150:153], v[198:201], v[68:71]
	v_mfma_f32_16x16x32_bf16 v[64:67], v[162:165], v[198:201], v[64:67]
	v_mfma_f32_16x16x32_bf16 v[116:119], v[154:157], v[178:181], v[116:119]
	v_mfma_f32_16x16x32_bf16 v[104:107], v[166:169], v[178:181], v[104:107]
	v_mfma_f32_16x16x32_bf16 v[96:99], v[154:157], v[186:189], v[96:99]
	v_mfma_f32_16x16x32_bf16 v[88:91], v[166:169], v[186:189], v[88:91]
	v_mfma_f32_16x16x32_bf16 v[80:83], v[154:157], v[194:197], v[80:83]
	v_mfma_f32_16x16x32_bf16 v[72:75], v[166:169], v[194:197], v[72:75]
	v_mfma_f32_16x16x32_bf16 v[68:71], v[154:157], v[202:205], v[68:71]
	v_mfma_f32_16x16x32_bf16 v[64:67], v[166:169], v[202:205], v[64:67]
	s_setprio 0
	s_barrier
	s_add_i32 s22, s88, s34
	v_lshl_add_u64 v[174:175], v[174:175], 0, s[40:41]
	s_mov_b32 m0, s22
	ds_read_b128 v[170:173], v161 offset:49152
	ds_read_b128 v[178:181], v161 offset:50176
	ds_read_b128 v[182:185], v161 offset:51200
	ds_read_b128 v[186:189], v161 offset:52224
	ds_read_b128 v[190:193], v161 offset:53248
	ds_read_b128 v[194:197], v161 offset:54272
	ds_read_b128 v[198:201], v161 offset:55296
	ds_read_b128 v[202:205], v161 offset:56320
	global_load_lds_dwordx4 v[174:175], off
	s_add_i32 m0, s22, 0x2000
	s_add_u32 s22, s26, 0x80080
	v_lshl_add_u64 v[174:175], v[206:207], 0, s[40:41]
	s_addc_u32 s23, s27, 0
	s_add_i32 s26, s89, s34
	global_load_lds_dwordx4 v[174:175], off
	v_lshl_add_u64 v[174:175], s[22:23], 0, v[176:177]
	s_mov_b32 m0, s26
	s_nop 0
	global_load_lds_dwordx4 v[174:175], off
	v_lshl_add_u64 v[174:175], s[22:23], 0, v[144:145]
	s_add_i32 m0, s26, 0x2000
	s_nop 0
	global_load_lds_dwordx4 v[174:175], off
	v_lshl_add_u64 v[174:175], v[208:209], 0, s[40:41]
	s_mov_b32 m0, s46
	s_nop 0
	global_load_lds_dwordx4 v[174:175], off
	v_lshl_add_u64 v[174:175], v[210:211], 0, s[40:41]
	s_mov_b32 m0, s47
	s_nop 0
	global_load_lds_dwordx4 v[174:175], off
	s_waitcnt vmcnt(8)
	s_waitcnt lgkmcnt(0)
	s_barrier
	s_setprio 1
	s_waitcnt lgkmcnt(0)
	v_mfma_f32_16x16x32_bf16 v[60:63], v[128:131], v[170:173], v[60:63]
	v_mfma_f32_16x16x32_bf16 v[56:59], v[136:139], v[170:173], v[56:59]
	v_mfma_f32_16x16x32_bf16 v[52:55], v[128:131], v[182:185], v[52:55]
	v_mfma_f32_16x16x32_bf16 v[44:47], v[136:139], v[182:185], v[44:47]
	v_mfma_f32_16x16x32_bf16 v[36:39], v[128:131], v[190:193], v[36:39]
	v_mfma_f32_16x16x32_bf16 v[28:31], v[136:139], v[190:193], v[28:31]
	v_mfma_f32_16x16x32_bf16 v[16:19], v[128:131], v[198:201], v[16:19]
	v_mfma_f32_16x16x32_bf16 v[8:11], v[136:139], v[198:201], v[8:11]
	v_mfma_f32_16x16x32_bf16 v[60:63], v[132:135], v[178:181], v[60:63]
	v_mfma_f32_16x16x32_bf16 v[56:59], v[140:143], v[178:181], v[56:59]
	v_mfma_f32_16x16x32_bf16 v[52:55], v[132:135], v[186:189], v[52:55]
	v_mfma_f32_16x16x32_bf16 v[44:47], v[140:143], v[186:189], v[44:47]
	v_mfma_f32_16x16x32_bf16 v[36:39], v[132:135], v[194:197], v[36:39]
	v_mfma_f32_16x16x32_bf16 v[28:31], v[140:143], v[194:197], v[28:31]
	v_mfma_f32_16x16x32_bf16 v[16:19], v[132:135], v[202:205], v[16:19]
	v_mfma_f32_16x16x32_bf16 v[8:11], v[140:143], v[202:205], v[8:11]
	v_mfma_f32_16x16x32_bf16 v[48:51], v[150:153], v[170:173], v[48:51]
	v_mfma_f32_16x16x32_bf16 v[40:43], v[162:165], v[170:173], v[40:43]
	v_mfma_f32_16x16x32_bf16 v[32:35], v[150:153], v[182:185], v[32:35]
	v_mfma_f32_16x16x32_bf16 v[24:27], v[162:165], v[182:185], v[24:27]
	v_mfma_f32_16x16x32_bf16 v[20:23], v[150:153], v[190:193], v[20:23]
	v_mfma_f32_16x16x32_bf16 v[12:15], v[162:165], v[190:193], v[12:15]
	v_mfma_f32_16x16x32_bf16 v[4:7], v[150:153], v[198:201], v[4:7]
	v_mfma_f32_16x16x32_bf16 v[0:3], v[162:165], v[198:201], v[0:3]
	v_mfma_f32_16x16x32_bf16 v[48:51], v[154:157], v[178:181], v[48:51]
	v_mfma_f32_16x16x32_bf16 v[40:43], v[166:169], v[178:181], v[40:43]
	v_mfma_f32_16x16x32_bf16 v[32:35], v[154:157], v[186:189], v[32:35]
	v_mfma_f32_16x16x32_bf16 v[24:27], v[166:169], v[186:189], v[24:27]
	v_mfma_f32_16x16x32_bf16 v[20:23], v[154:157], v[194:197], v[20:23]
	v_mfma_f32_16x16x32_bf16 v[12:15], v[166:169], v[194:197], v[12:15]
	v_mfma_f32_16x16x32_bf16 v[4:7], v[154:157], v[202:205], v[4:7]
	v_mfma_f32_16x16x32_bf16 v[0:3], v[166:169], v[202:205], v[0:3]
	s_setprio 0
	s_barrier
	s_add_u32 s49, s49, 0x100
	s_addc_u32 s96, s96, 0
	s_cmp_ge_u32 s97, s7
	s_mov_b64 s[22:23], s[24:25]
	s_mov_b32 s26, s97
	s_cbranch_scc0 .LBB0_1261
	s_and_b64 vcc, exec, s[4:5]
	s_cbranch_vccz .LBB0_1264
	s_barrier

.LBB0_1383:
	s_add_u32 s34, s10, 0xfff80080
	s_addc_u32 s35, s11, -1
	s_add_i32 s88, 0, 0x10000
	s_cmp_eq_u32 s49, 28
	s_cselect_b32 s47, s7, s35
	s_cselect_b32 s46, s25, s34
	s_cselect_b32 s35, s23, s48
	s_cselect_b32 s34, vcc_lo, vcc_hi
	s_add_i32 s89, 0, 0x14000
	v_add_u32_e32 v140, s88, v240
	v_add_u32_e32 v156, s89, v240
	ds_read_b128 v[128:131], v140
	ds_read_b128 v[132:135], v140 offset:1024
	ds_read_b128 v[136:139], v140 offset:2048
	ds_read_b128 v[140:143], v140 offset:3072
	ds_read_b128 v[144:147], v156
	ds_read_b128 v[148:151], v156 offset:1024
	ds_read_b128 v[152:155], v156 offset:2048
	ds_read_b128 v[156:159], v156 offset:3072
	v_lshl_add_u64 v[212:213], s[10:11], 0, v[184:185]
	s_add_i32 m0, s31, 0xc000
	ds_read_b128 v[188:191], v241
	ds_read_b128 v[192:195], v241 offset:1024
	ds_read_b128 v[196:199], v241 offset:2048
	ds_read_b128 v[200:203], v241 offset:3072
	ds_read_b128 v[204:207], v241 offset:4096
	ds_read_b128 v[208:211], v241 offset:5120
	ds_read_b128 v[220:223], v241 offset:6144
	ds_read_b128 v[242:245], v241 offset:7168
	global_load_lds_dwordx4 v[212:213], off
	v_lshl_add_u64 v[212:213], s[10:11], 0, v[186:187]
	s_add_i32 m0, s31, 0xe000
	s_nop 0
	global_load_lds_dwordx4 v[212:213], off
	s_waitcnt vmcnt(8)
	s_waitcnt lgkmcnt(0)
	s_barrier
	s_setprio 1
	s_waitcnt lgkmcnt(0)
	v_mfma_f32_16x16x32_bf16 v[116:119], v[128:131], v[188:191], v[116:119]
	v_mfma_f32_16x16x32_bf16 v[84:87], v[136:139], v[188:191], v[84:87]
	v_mfma_f32_16x16x32_bf16 v[124:127], v[128:131], v[196:199], v[124:127]
	v_mfma_f32_16x16x32_bf16 v[108:111], v[136:139], v[196:199], v[108:111]
	v_mfma_f32_16x16x32_bf16 v[120:123], v[128:131], v[204:207], v[120:123]
	v_mfma_f32_16x16x32_bf16 v[92:95], v[136:139], v[204:207], v[92:95]
	v_mfma_f32_16x16x32_bf16 v[112:115], v[128:131], v[220:223], v[112:115]
	v_mfma_f32_16x16x32_bf16 v[80:83], v[136:139], v[220:223], v[80:83]
	v_mfma_f32_16x16x32_bf16 v[116:119], v[132:135], v[192:195], v[116:119]
	v_mfma_f32_16x16x32_bf16 v[84:87], v[140:143], v[192:195], v[84:87]
	v_mfma_f32_16x16x32_bf16 v[124:127], v[132:135], v[200:203], v[124:127]
	v_mfma_f32_16x16x32_bf16 v[108:111], v[140:143], v[200:203], v[108:111]
	v_mfma_f32_16x16x32_bf16 v[120:123], v[132:135], v[208:211], v[120:123]
	v_mfma_f32_16x16x32_bf16 v[92:95], v[140:143], v[208:211], v[92:95]
	v_mfma_f32_16x16x32_bf16 v[112:115], v[132:135], v[242:245], v[112:115]
	v_mfma_f32_16x16x32_bf16 v[80:83], v[140:143], v[242:245], v[80:83]
	v_mfma_f32_16x16x32_bf16 v[52:55], v[144:147], v[188:191], v[52:55]
	v_mfma_f32_16x16x32_bf16 v[20:23], v[152:155], v[188:191], v[20:23]
	v_mfma_f32_16x16x32_bf16 v[60:63], v[144:147], v[196:199], v[60:63]
	v_mfma_f32_16x16x32_bf16 v[28:31], v[152:155], v[196:199], v[28:31]
	v_mfma_f32_16x16x32_bf16 v[56:59], v[144:147], v[204:207], v[56:59]
	v_mfma_f32_16x16x32_bf16 v[24:27], v[152:155], v[204:207], v[24:27]
	v_mfma_f32_16x16x32_bf16 v[48:51], v[144:147], v[220:223], v[48:51]
	v_mfma_f32_16x16x32_bf16 v[16:19], v[152:155], v[220:223], v[16:19]
	v_mfma_f32_16x16x32_bf16 v[52:55], v[148:151], v[192:195], v[52:55]
	v_mfma_f32_16x16x32_bf16 v[20:23], v[156:159], v[192:195], v[20:23]
	v_mfma_f32_16x16x32_bf16 v[60:63], v[148:151], v[200:203], v[60:63]
	v_mfma_f32_16x16x32_bf16 v[28:31], v[156:159], v[200:203], v[28:31]
	v_mfma_f32_16x16x32_bf16 v[56:59], v[148:151], v[208:211], v[56:59]
	v_mfma_f32_16x16x32_bf16 v[24:27], v[156:159], v[208:211], v[24:27]
	v_mfma_f32_16x16x32_bf16 v[48:51], v[148:151], v[242:245], v[48:51]
	v_mfma_f32_16x16x32_bf16 v[16:19], v[156:159], v[242:245], v[16:19]
	s_setprio 0
	s_barrier
	s_add_i32 s88, s88, s37
	v_lshl_add_u64 v[212:213], s[34:35], 0, v[176:177]
	s_mov_b32 m0, s88
	ds_read_b128 v[188:191], v241 offset:16384
	ds_read_b128 v[192:195], v241 offset:17408
	ds_read_b128 v[196:199], v241 offset:18432
	ds_read_b128 v[200:203], v241 offset:19456
	ds_read_b128 v[204:207], v241 offset:20480
	ds_read_b128 v[208:211], v241 offset:21504
	ds_read_b128 v[220:223], v241 offset:22528
	ds_read_b128 v[242:245], v241 offset:23552
	global_load_lds_dwordx4 v[212:213], off
	s_add_i32 m0, s88, 0x2000
	s_add_u32 s96, s34, 0x80000
	v_lshl_add_u64 v[224:225], s[34:35], 0, v[164:165]
	s_addc_u32 s97, s35, 0
	s_add_i32 s88, s89, s37
	global_load_lds_dwordx4 v[224:225], off
	v_lshl_add_u64 v[228:229], s[96:97], 0, v[176:177]
	s_mov_b32 m0, s88
	v_lshl_add_u64 v[246:247], s[46:47], 0, v[162:163]
	global_load_lds_dwordx4 v[228:229], off
	v_lshl_add_u64 v[228:229], s[96:97], 0, v[164:165]
	s_add_i32 m0, s88, 0x2000
	s_nop 0
	global_load_lds_dwordx4 v[228:229], off
	v_lshl_add_u64 v[228:229], s[46:47], 0, v[160:161]
	s_mov_b32 m0, s31
	s_nop 0
	global_load_lds_dwordx4 v[228:229], off
	s_mov_b32 m0, s8
	s_nop 0
	global_load_lds_dwordx4 v[246:247], off
	s_waitcnt vmcnt(8)
	s_waitcnt lgkmcnt(0)
	s_barrier
	s_setprio 1
	s_waitcnt lgkmcnt(0)
	v_mfma_f32_16x16x32_bf16 v[100:103], v[128:131], v[188:191], v[100:103]
	v_mfma_f32_16x16x32_bf16 v[72:75], v[136:139], v[188:191], v[72:75]
	v_mfma_f32_16x16x32_bf16 v[104:107], v[128:131], v[196:199], v[104:107]
	v_mfma_f32_16x16x32_bf16 v[76:79], v[136:139], v[196:199], v[76:79]
	v_mfma_f32_16x16x32_bf16 v[96:99], v[128:131], v[204:207], v[96:99]
	v_mfma_f32_16x16x32_bf16 v[68:71], v[136:139], v[204:207], v[68:71]
	v_mfma_f32_16x16x32_bf16 v[88:91], v[128:131], v[220:223], v[88:91]
	v_mfma_f32_16x16x32_bf16 v[64:67], v[136:139], v[220:223], v[64:67]
	v_mfma_f32_16x16x32_bf16 v[100:103], v[132:135], v[192:195], v[100:103]
	v_mfma_f32_16x16x32_bf16 v[72:75], v[140:143], v[192:195], v[72:75]
	v_mfma_f32_16x16x32_bf16 v[104:107], v[132:135], v[200:203], v[104:107]
	v_mfma_f32_16x16x32_bf16 v[76:79], v[140:143], v[200:203], v[76:79]
	v_mfma_f32_16x16x32_bf16 v[96:99], v[132:135], v[208:211], v[96:99]
	v_mfma_f32_16x16x32_bf16 v[68:71], v[140:143], v[208:211], v[68:71]
	v_mfma_f32_16x16x32_bf16 v[88:91], v[132:135], v[242:245], v[88:91]
	v_mfma_f32_16x16x32_bf16 v[64:67], v[140:143], v[242:245], v[64:67]
	v_mfma_f32_16x16x32_bf16 v[44:47], v[144:147], v[188:191], v[44:47]
	v_mfma_f32_16x16x32_bf16 v[8:11], v[152:155], v[188:191], v[8:11]
	v_mfma_f32_16x16x32_bf16 v[40:43], v[144:147], v[196:199], v[40:43]
	v_mfma_f32_16x16x32_bf16 v[12:15], v[152:155], v[196:199], v[12:15]
	v_mfma_f32_16x16x32_bf16 v[36:39], v[144:147], v[204:207], v[36:39]
	v_mfma_f32_16x16x32_bf16 v[4:7], v[152:155], v[204:207], v[4:7]
	v_mfma_f32_16x16x32_bf16 v[32:35], v[144:147], v[220:223], v[32:35]
	v_mfma_f32_16x16x32_bf16 v[0:3], v[152:155], v[220:223], v[0:3]
	v_mfma_f32_16x16x32_bf16 v[44:47], v[148:151], v[192:195], v[44:47]
	v_mfma_f32_16x16x32_bf16 v[8:11], v[156:159], v[192:195], v[8:11]
	v_mfma_f32_16x16x32_bf16 v[40:43], v[148:151], v[200:203], v[40:43]
	v_mfma_f32_16x16x32_bf16 v[12:15], v[156:159], v[200:203], v[12:15]
	v_mfma_f32_16x16x32_bf16 v[36:39], v[148:151], v[208:211], v[36:39]
	v_mfma_f32_16x16x32_bf16 v[4:7], v[156:159], v[208:211], v[4:7]
	v_mfma_f32_16x16x32_bf16 v[32:35], v[148:151], v[242:245], v[32:35]
	v_mfma_f32_16x16x32_bf16 v[0:3], v[156:159], v[242:245], v[0:3]
	s_setprio 0
	s_barrier
	s_add_i32 s88, 0, 0x18000
	s_add_i32 s89, 0, 0x1c000
	v_add_u32_e32 v140, s88, v240
	v_add_u32_e32 v156, s89, v240
	ds_read_b128 v[128:131], v140
	ds_read_b128 v[132:135], v140 offset:1024
	ds_read_b128 v[136:139], v140 offset:2048
	ds_read_b128 v[140:143], v140 offset:3072
	ds_read_b128 v[144:147], v156
	ds_read_b128 v[148:151], v156 offset:1024
	ds_read_b128 v[152:155], v156 offset:2048
	ds_read_b128 v[156:159], v156 offset:3072
	s_add_u32 s46, s46, 0x80000
	s_addc_u32 s47, s47, 0
	s_mov_b32 m0, s9
	v_lshl_add_u64 v[248:249], s[46:47], 0, v[160:161]
	ds_read_b128 v[188:191], v241 offset:32768
	ds_read_b128 v[192:195], v241 offset:33792
	ds_read_b128 v[196:199], v241 offset:34816
	ds_read_b128 v[200:203], v241 offset:35840
	ds_read_b128 v[204:207], v241 offset:36864
	ds_read_b128 v[208:211], v241 offset:37888
	ds_read_b128 v[220:223], v241 offset:38912
	ds_read_b128 v[242:245], v241 offset:39936
	global_load_lds_dwordx4 v[248:249], off
	v_lshl_add_u64 v[248:249], s[46:47], 0, v[162:163]
	s_mov_b32 m0, s92
	s_nop 0
	global_load_lds_dwordx4 v[248:249], off
	s_waitcnt vmcnt(8)
	s_waitcnt lgkmcnt(0)
	s_barrier
	s_setprio 1
	s_waitcnt lgkmcnt(0)
	v_mfma_f32_16x16x32_bf16 v[116:119], v[128:131], v[188:191], v[116:119]
	v_mfma_f32_16x16x32_bf16 v[84:87], v[136:139], v[188:191], v[84:87]
	v_mfma_f32_16x16x32_bf16 v[124:127], v[128:131], v[196:199], v[124:127]
	v_mfma_f32_16x16x32_bf16 v[108:111], v[136:139], v[196:199], v[108:111]
	v_mfma_f32_16x16x32_bf16 v[120:123], v[128:131], v[204:207], v[120:123]
	v_mfma_f32_16x16x32_bf16 v[92:95], v[136:139], v[204:207], v[92:95]
	v_mfma_f32_16x16x32_bf16 v[112:115], v[128:131], v[220:223], v[112:115]
	v_mfma_f32_16x16x32_bf16 v[80:83], v[136:139], v[220:223], v[80:83]
	v_mfma_f32_16x16x32_bf16 v[116:119], v[132:135], v[192:195], v[116:119]
	v_mfma_f32_16x16x32_bf16 v[84:87], v[140:143], v[192:195], v[84:87]
	v_mfma_f32_16x16x32_bf16 v[124:127], v[132:135], v[200:203], v[124:127]
	v_mfma_f32_16x16x32_bf16 v[108:111], v[140:143], v[200:203], v[108:111]
	v_mfma_f32_16x16x32_bf16 v[120:123], v[132:135], v[208:211], v[120:123]
	v_mfma_f32_16x16x32_bf16 v[92:95], v[140:143], v[208:211], v[92:95]
	v_mfma_f32_16x16x32_bf16 v[112:115], v[132:135], v[242:245], v[112:115]
	v_mfma_f32_16x16x32_bf16 v[80:83], v[140:143], v[242:245], v[80:83]
	v_mfma_f32_16x16x32_bf16 v[52:55], v[144:147], v[188:191], v[52:55]
	v_mfma_f32_16x16x32_bf16 v[20:23], v[152:155], v[188:191], v[20:23]
	v_mfma_f32_16x16x32_bf16 v[60:63], v[144:147], v[196:199], v[60:63]
	v_mfma_f32_16x16x32_bf16 v[28:31], v[152:155], v[196:199], v[28:31]
	v_mfma_f32_16x16x32_bf16 v[56:59], v[144:147], v[204:207], v[56:59]
	v_mfma_f32_16x16x32_bf16 v[24:27], v[152:155], v[204:207], v[24:27]
	v_mfma_f32_16x16x32_bf16 v[48:51], v[144:147], v[220:223], v[48:51]
	v_mfma_f32_16x16x32_bf16 v[16:19], v[152:155], v[220:223], v[16:19]
	v_mfma_f32_16x16x32_bf16 v[52:55], v[148:151], v[192:195], v[52:55]
	v_mfma_f32_16x16x32_bf16 v[20:23], v[156:159], v[192:195], v[20:23]
	v_mfma_f32_16x16x32_bf16 v[60:63], v[148:151], v[200:203], v[60:63]
	v_mfma_f32_16x16x32_bf16 v[28:31], v[156:159], v[200:203], v[28:31]
	v_mfma_f32_16x16x32_bf16 v[56:59], v[148:151], v[208:211], v[56:59]
	v_mfma_f32_16x16x32_bf16 v[24:27], v[156:159], v[208:211], v[24:27]
	v_mfma_f32_16x16x32_bf16 v[48:51], v[148:151], v[242:245], v[48:51]
	v_mfma_f32_16x16x32_bf16 v[16:19], v[156:159], v[242:245], v[16:19]
	s_setprio 0
	s_barrier
	s_add_i32 s46, s88, s37
	v_lshl_add_u64 v[212:213], v[212:213], 0, s[40:41]
	s_mov_b32 m0, s46
	ds_read_b128 v[188:191], v241 offset:49152
	ds_read_b128 v[192:195], v241 offset:50176
	ds_read_b128 v[196:199], v241 offset:51200
	ds_read_b128 v[200:203], v241 offset:52224
	ds_read_b128 v[204:207], v241 offset:53248
	ds_read_b128 v[208:211], v241 offset:54272
	ds_read_b128 v[220:223], v241 offset:55296
	ds_read_b128 v[242:245], v241 offset:56320
	global_load_lds_dwordx4 v[212:213], off
	s_add_i32 m0, s46, 0x2000
	s_add_u32 s34, s34, 0x80080
	v_lshl_add_u64 v[212:213], v[224:225], 0, s[40:41]
	s_addc_u32 s35, s35, 0
	s_add_i32 s46, s89, s37
	global_load_lds_dwordx4 v[212:213], off
	v_lshl_add_u64 v[212:213], s[34:35], 0, v[176:177]
	s_mov_b32 m0, s46
	s_nop 0
	global_load_lds_dwordx4 v[212:213], off
	v_lshl_add_u64 v[212:213], s[34:35], 0, v[164:165]
	s_add_i32 m0, s46, 0x2000
	s_nop 0
	global_load_lds_dwordx4 v[212:213], off
	v_lshl_add_u64 v[212:213], v[228:229], 0, s[40:41]
	s_mov_b32 m0, s56
	s_nop 0
	global_load_lds_dwordx4 v[212:213], off
	v_lshl_add_u64 v[212:213], v[246:247], 0, s[40:41]
	s_mov_b32 m0, s57
	s_nop 0
	global_load_lds_dwordx4 v[212:213], off
	s_waitcnt vmcnt(8)
	s_waitcnt lgkmcnt(0)
	s_barrier
	s_setprio 1
	s_waitcnt lgkmcnt(0)
	v_mfma_f32_16x16x32_bf16 v[100:103], v[128:131], v[188:191], v[100:103]
	v_mfma_f32_16x16x32_bf16 v[72:75], v[136:139], v[188:191], v[72:75]
	v_mfma_f32_16x16x32_bf16 v[104:107], v[128:131], v[196:199], v[104:107]
	v_mfma_f32_16x16x32_bf16 v[76:79], v[136:139], v[196:199], v[76:79]
	v_mfma_f32_16x16x32_bf16 v[96:99], v[128:131], v[204:207], v[96:99]
	v_mfma_f32_16x16x32_bf16 v[68:71], v[136:139], v[204:207], v[68:71]
	v_mfma_f32_16x16x32_bf16 v[88:91], v[128:131], v[220:223], v[88:91]
	v_mfma_f32_16x16x32_bf16 v[64:67], v[136:139], v[220:223], v[64:67]
	v_mfma_f32_16x16x32_bf16 v[100:103], v[132:135], v[192:195], v[100:103]
	v_mfma_f32_16x16x32_bf16 v[72:75], v[140:143], v[192:195], v[72:75]
	v_mfma_f32_16x16x32_bf16 v[104:107], v[132:135], v[200:203], v[104:107]
	v_mfma_f32_16x16x32_bf16 v[76:79], v[140:143], v[200:203], v[76:79]
	v_mfma_f32_16x16x32_bf16 v[96:99], v[132:135], v[208:211], v[96:99]
	v_mfma_f32_16x16x32_bf16 v[68:71], v[140:143], v[208:211], v[68:71]
	v_mfma_f32_16x16x32_bf16 v[88:91], v[132:135], v[242:245], v[88:91]
	v_mfma_f32_16x16x32_bf16 v[64:67], v[140:143], v[242:245], v[64:67]
	v_mfma_f32_16x16x32_bf16 v[44:47], v[144:147], v[188:191], v[44:47]
	v_mfma_f32_16x16x32_bf16 v[8:11], v[152:155], v[188:191], v[8:11]
	v_mfma_f32_16x16x32_bf16 v[40:43], v[144:147], v[196:199], v[40:43]
	v_mfma_f32_16x16x32_bf16 v[12:15], v[152:155], v[196:199], v[12:15]
	v_mfma_f32_16x16x32_bf16 v[36:39], v[144:147], v[204:207], v[36:39]
	v_mfma_f32_16x16x32_bf16 v[4:7], v[152:155], v[204:207], v[4:7]
	v_mfma_f32_16x16x32_bf16 v[32:35], v[144:147], v[220:223], v[32:35]
	v_mfma_f32_16x16x32_bf16 v[0:3], v[152:155], v[220:223], v[0:3]
	v_mfma_f32_16x16x32_bf16 v[44:47], v[148:151], v[192:195], v[44:47]
	v_mfma_f32_16x16x32_bf16 v[8:11], v[156:159], v[192:195], v[8:11]
	v_mfma_f32_16x16x32_bf16 v[40:43], v[148:151], v[200:203], v[40:43]
	v_mfma_f32_16x16x32_bf16 v[12:15], v[156:159], v[200:203], v[12:15]
	v_mfma_f32_16x16x32_bf16 v[36:39], v[148:151], v[208:211], v[36:39]
	v_mfma_f32_16x16x32_bf16 v[4:7], v[156:159], v[208:211], v[4:7]
	v_mfma_f32_16x16x32_bf16 v[32:35], v[148:151], v[242:245], v[32:35]
	v_mfma_f32_16x16x32_bf16 v[0:3], v[156:159], v[242:245], v[0:3]
	s_setprio 0
	s_barrier
	s_add_i32 s49, s49, 2
	s_add_u32 s10, s10, 0x100
	s_addc_u32 s11, s11, 0
	s_add_u32 vcc_hi, vcc_hi, 0x100
	s_addc_u32 s48, s48, 0
	s_cmp_gt_u32 s49, 29
	s_cbranch_scc0 .LBB0_1383
	s_and_b64 vcc, exec, s[16:17]
	s_cbranch_vccz .LBB0_1386
	s_barrier

.LBB0_1801:
	s_add_i32 s97, s22, 2
	s_add_u32 s20, s18, 0x100
	s_addc_u32 s21, s19, 0
	s_add_i32 s88, 0, 0x10000
	s_cmp_eq_u32 s48, s22
	s_cselect_b32 s25, s15, s21
	s_cselect_b32 s24, s14, s20
	s_cselect_b32 s23, s17, s96
	s_cselect_b32 s22, s16, s49
	s_add_i32 s89, 0, 0x14000
	v_add_u32_e32 v140, s88, v158
	v_add_u32_e32 v154, s89, v158
	ds_read_b128 v[128:131], v140
	ds_read_b128 v[132:135], v140 offset:1024
	ds_read_b128 v[136:139], v140 offset:2048
	ds_read_b128 v[140:143], v140 offset:3072
	ds_read_b128 v[150:153], v154
	ds_read_b128 v[160:163], v154 offset:1024
	ds_read_b128 v[164:167], v154 offset:2048
	ds_read_b128 v[168:171], v154 offset:3072
	v_lshl_add_u64 v[154:155], s[18:19], 0, v[146:147]
	s_add_i32 m0, s28, 0xc000
	ds_read_b128 v[172:175], v159
	ds_read_b128 v[178:181], v159 offset:1024
	ds_read_b128 v[182:185], v159 offset:2048
	ds_read_b128 v[186:189], v159 offset:3072
	ds_read_b128 v[190:193], v159 offset:4096
	ds_read_b128 v[194:197], v159 offset:5120
	ds_read_b128 v[198:201], v159 offset:6144
	ds_read_b128 v[202:205], v159 offset:7168
	global_load_lds_dwordx4 v[154:155], off
	v_lshl_add_u64 v[154:155], s[18:19], 0, v[148:149]
	s_add_i32 m0, s28, 0xe000
	s_nop 0
	global_load_lds_dwordx4 v[154:155], off
	s_waitcnt vmcnt(8)
	s_waitcnt lgkmcnt(0)
	s_barrier
	s_setprio 1
	s_waitcnt lgkmcnt(0)
	v_mfma_f32_16x16x32_bf16 v[124:127], v[128:131], v[172:175], v[124:127]
	v_mfma_f32_16x16x32_bf16 v[120:123], v[136:139], v[172:175], v[120:123]
	v_mfma_f32_16x16x32_bf16 v[116:119], v[128:131], v[182:185], v[116:119]
	v_mfma_f32_16x16x32_bf16 v[112:115], v[136:139], v[182:185], v[112:115]
	v_mfma_f32_16x16x32_bf16 v[108:111], v[128:131], v[190:193], v[108:111]
	v_mfma_f32_16x16x32_bf16 v[100:103], v[136:139], v[190:193], v[100:103]
	v_mfma_f32_16x16x32_bf16 v[92:95], v[128:131], v[198:201], v[92:95]
	v_mfma_f32_16x16x32_bf16 v[72:75], v[136:139], v[198:201], v[72:75]
	v_mfma_f32_16x16x32_bf16 v[124:127], v[132:135], v[178:181], v[124:127]
	v_mfma_f32_16x16x32_bf16 v[120:123], v[140:143], v[178:181], v[120:123]
	v_mfma_f32_16x16x32_bf16 v[116:119], v[132:135], v[186:189], v[116:119]
	v_mfma_f32_16x16x32_bf16 v[112:115], v[140:143], v[186:189], v[112:115]
	v_mfma_f32_16x16x32_bf16 v[108:111], v[132:135], v[194:197], v[108:111]
	v_mfma_f32_16x16x32_bf16 v[100:103], v[140:143], v[194:197], v[100:103]
	v_mfma_f32_16x16x32_bf16 v[92:95], v[132:135], v[202:205], v[92:95]
	v_mfma_f32_16x16x32_bf16 v[72:75], v[140:143], v[202:205], v[72:75]
	v_mfma_f32_16x16x32_bf16 v[104:107], v[150:153], v[172:175], v[104:107]
	v_mfma_f32_16x16x32_bf16 v[96:99], v[164:167], v[172:175], v[96:99]
	v_mfma_f32_16x16x32_bf16 v[88:91], v[150:153], v[182:185], v[88:91]
	v_mfma_f32_16x16x32_bf16 v[84:87], v[164:167], v[182:185], v[84:87]
	v_mfma_f32_16x16x32_bf16 v[80:83], v[150:153], v[190:193], v[80:83]
	v_mfma_f32_16x16x32_bf16 v[76:79], v[164:167], v[190:193], v[76:79]
	v_mfma_f32_16x16x32_bf16 v[68:71], v[150:153], v[198:201], v[68:71]
	v_mfma_f32_16x16x32_bf16 v[64:67], v[164:167], v[198:201], v[64:67]
	v_mfma_f32_16x16x32_bf16 v[104:107], v[160:163], v[178:181], v[104:107]
	v_mfma_f32_16x16x32_bf16 v[96:99], v[168:171], v[178:181], v[96:99]
	v_mfma_f32_16x16x32_bf16 v[88:91], v[160:163], v[186:189], v[88:91]
	v_mfma_f32_16x16x32_bf16 v[84:87], v[168:171], v[186:189], v[84:87]
	v_mfma_f32_16x16x32_bf16 v[80:83], v[160:163], v[194:197], v[80:83]
	v_mfma_f32_16x16x32_bf16 v[76:79], v[168:171], v[194:197], v[76:79]
	v_mfma_f32_16x16x32_bf16 v[68:71], v[160:163], v[202:205], v[68:71]
	v_mfma_f32_16x16x32_bf16 v[64:67], v[168:171], v[202:205], v[64:67]
	s_setprio 0
	s_barrier
	s_add_i32 s18, s88, s27
	v_lshl_add_u64 v[154:155], s[22:23], 0, v[176:177]
	s_mov_b32 m0, s18
	ds_read_b128 v[172:175], v159 offset:16384
	ds_read_b128 v[178:181], v159 offset:17408
	ds_read_b128 v[182:185], v159 offset:18432
	ds_read_b128 v[186:189], v159 offset:19456
	ds_read_b128 v[190:193], v159 offset:20480
	ds_read_b128 v[194:197], v159 offset:21504
	ds_read_b128 v[198:201], v159 offset:22528
	ds_read_b128 v[202:205], v159 offset:23552
	global_load_lds_dwordx4 v[154:155], off
	s_add_i32 m0, s18, 0x2000
	s_add_u32 s18, s22, 0x160000
	v_lshl_add_u64 v[206:207], s[22:23], 0, v[144:145]
	s_addc_u32 s19, s23, 0
	s_add_i32 s88, s89, s27
	global_load_lds_dwordx4 v[206:207], off
	v_lshl_add_u64 v[208:209], s[18:19], 0, v[176:177]
	s_mov_b32 m0, s88
	v_lshl_add_u64 v[210:211], s[24:25], 0, v[144:145]
	global_load_lds_dwordx4 v[208:209], off
	v_lshl_add_u64 v[208:209], s[18:19], 0, v[144:145]
	s_add_i32 m0, s88, 0x2000
	s_nop 0
	global_load_lds_dwordx4 v[208:209], off
	v_lshl_add_u64 v[208:209], s[24:25], 0, v[176:177]
	s_mov_b32 m0, s28
	s_nop 0
	global_load_lds_dwordx4 v[208:209], off
	s_mov_b32 m0, s29
	s_nop 0
	global_load_lds_dwordx4 v[210:211], off
	s_waitcnt vmcnt(8)
	s_waitcnt lgkmcnt(0)
	s_barrier
	s_setprio 1
	s_waitcnt lgkmcnt(0)
	v_mfma_f32_16x16x32_bf16 v[60:63], v[128:131], v[172:175], v[60:63]
	v_mfma_f32_16x16x32_bf16 v[56:59], v[136:139], v[172:175], v[56:59]
	v_mfma_f32_16x16x32_bf16 v[52:55], v[128:131], v[182:185], v[52:55]
	v_mfma_f32_16x16x32_bf16 v[48:51], v[136:139], v[182:185], v[48:51]
	v_mfma_f32_16x16x32_bf16 v[44:47], v[128:131], v[190:193], v[44:47]
	v_mfma_f32_16x16x32_bf16 v[32:35], v[136:139], v[190:193], v[32:35]
	v_mfma_f32_16x16x32_bf16 v[16:19], v[128:131], v[198:201], v[16:19]
	v_mfma_f32_16x16x32_bf16 v[8:11], v[136:139], v[198:201], v[8:11]
	v_mfma_f32_16x16x32_bf16 v[60:63], v[132:135], v[178:181], v[60:63]
	v_mfma_f32_16x16x32_bf16 v[56:59], v[140:143], v[178:181], v[56:59]
	v_mfma_f32_16x16x32_bf16 v[52:55], v[132:135], v[186:189], v[52:55]
	v_mfma_f32_16x16x32_bf16 v[48:51], v[140:143], v[186:189], v[48:51]
	v_mfma_f32_16x16x32_bf16 v[44:47], v[132:135], v[194:197], v[44:47]
	v_mfma_f32_16x16x32_bf16 v[32:35], v[140:143], v[194:197], v[32:35]
	v_mfma_f32_16x16x32_bf16 v[16:19], v[132:135], v[202:205], v[16:19]
	v_mfma_f32_16x16x32_bf16 v[8:11], v[140:143], v[202:205], v[8:11]
	v_mfma_f32_16x16x32_bf16 v[40:43], v[150:153], v[172:175], v[40:43]
	v_mfma_f32_16x16x32_bf16 v[36:39], v[164:167], v[172:175], v[36:39]
	v_mfma_f32_16x16x32_bf16 v[28:31], v[150:153], v[182:185], v[28:31]
	v_mfma_f32_16x16x32_bf16 v[24:27], v[164:167], v[182:185], v[24:27]
	v_mfma_f32_16x16x32_bf16 v[20:23], v[150:153], v[190:193], v[20:23]
	v_mfma_f32_16x16x32_bf16 v[12:15], v[164:167], v[190:193], v[12:15]
	v_mfma_f32_16x16x32_bf16 v[4:7], v[150:153], v[198:201], v[4:7]
	v_mfma_f32_16x16x32_bf16 v[0:3], v[164:167], v[198:201], v[0:3]
	v_mfma_f32_16x16x32_bf16 v[40:43], v[160:163], v[178:181], v[40:43]
	v_mfma_f32_16x16x32_bf16 v[36:39], v[168:171], v[178:181], v[36:39]
	v_mfma_f32_16x16x32_bf16 v[28:31], v[160:163], v[186:189], v[28:31]
	v_mfma_f32_16x16x32_bf16 v[24:27], v[168:171], v[186:189], v[24:27]
	v_mfma_f32_16x16x32_bf16 v[20:23], v[160:163], v[194:197], v[20:23]
	v_mfma_f32_16x16x32_bf16 v[12:15], v[168:171], v[194:197], v[12:15]
	v_mfma_f32_16x16x32_bf16 v[4:7], v[160:163], v[202:205], v[4:7]
	v_mfma_f32_16x16x32_bf16 v[0:3], v[168:171], v[202:205], v[0:3]
	s_setprio 0
	s_barrier
	s_add_i32 s88, 0, 0x18000
	s_add_i32 s89, 0, 0x1c000
	v_add_u32_e32 v140, s88, v158
	v_add_u32_e32 v168, s89, v158
	ds_read_b128 v[128:131], v140
	ds_read_b128 v[132:135], v140 offset:1024
	ds_read_b128 v[136:139], v140 offset:2048
	ds_read_b128 v[140:143], v140 offset:3072
	ds_read_b128 v[150:153], v168
	ds_read_b128 v[160:163], v168 offset:1024
	ds_read_b128 v[164:167], v168 offset:2048
	ds_read_b128 v[168:171], v168 offset:3072
	s_add_u32 s18, s24, 0x160000
	s_addc_u32 s19, s25, 0
	s_mov_b32 m0, s30
	v_lshl_add_u64 v[212:213], s[18:19], 0, v[176:177]
	ds_read_b128 v[172:175], v159 offset:32768
	ds_read_b128 v[178:181], v159 offset:33792
	ds_read_b128 v[182:185], v159 offset:34816
	ds_read_b128 v[186:189], v159 offset:35840
	ds_read_b128 v[190:193], v159 offset:36864
	ds_read_b128 v[194:197], v159 offset:37888
	ds_read_b128 v[198:201], v159 offset:38912
	ds_read_b128 v[202:205], v159 offset:39936
	global_load_lds_dwordx4 v[212:213], off
	v_lshl_add_u64 v[212:213], s[18:19], 0, v[144:145]
	s_mov_b32 m0, s31
	s_nop 0
	global_load_lds_dwordx4 v[212:213], off
	s_waitcnt vmcnt(8)
	s_waitcnt lgkmcnt(0)
	s_barrier
	s_setprio 1
	s_waitcnt lgkmcnt(0)
	v_mfma_f32_16x16x32_bf16 v[124:127], v[128:131], v[172:175], v[124:127]
	v_mfma_f32_16x16x32_bf16 v[120:123], v[136:139], v[172:175], v[120:123]
	v_mfma_f32_16x16x32_bf16 v[116:119], v[128:131], v[182:185], v[116:119]
	v_mfma_f32_16x16x32_bf16 v[112:115], v[136:139], v[182:185], v[112:115]
	v_mfma_f32_16x16x32_bf16 v[108:111], v[128:131], v[190:193], v[108:111]
	v_mfma_f32_16x16x32_bf16 v[100:103], v[136:139], v[190:193], v[100:103]
	v_mfma_f32_16x16x32_bf16 v[92:95], v[128:131], v[198:201], v[92:95]
	v_mfma_f32_16x16x32_bf16 v[72:75], v[136:139], v[198:201], v[72:75]
	v_mfma_f32_16x16x32_bf16 v[124:127], v[132:135], v[178:181], v[124:127]
	v_mfma_f32_16x16x32_bf16 v[120:123], v[140:143], v[178:181], v[120:123]
	v_mfma_f32_16x16x32_bf16 v[116:119], v[132:135], v[186:189], v[116:119]
	v_mfma_f32_16x16x32_bf16 v[112:115], v[140:143], v[186:189], v[112:115]
	v_mfma_f32_16x16x32_bf16 v[108:111], v[132:135], v[194:197], v[108:111]
	v_mfma_f32_16x16x32_bf16 v[100:103], v[140:143], v[194:197], v[100:103]
	v_mfma_f32_16x16x32_bf16 v[92:95], v[132:135], v[202:205], v[92:95]
	v_mfma_f32_16x16x32_bf16 v[72:75], v[140:143], v[202:205], v[72:75]
	v_mfma_f32_16x16x32_bf16 v[104:107], v[150:153], v[172:175], v[104:107]
	v_mfma_f32_16x16x32_bf16 v[96:99], v[164:167], v[172:175], v[96:99]
	v_mfma_f32_16x16x32_bf16 v[88:91], v[150:153], v[182:185], v[88:91]
	v_mfma_f32_16x16x32_bf16 v[84:87], v[164:167], v[182:185], v[84:87]
	v_mfma_f32_16x16x32_bf16 v[80:83], v[150:153], v[190:193], v[80:83]
	v_mfma_f32_16x16x32_bf16 v[76:79], v[164:167], v[190:193], v[76:79]
	v_mfma_f32_16x16x32_bf16 v[68:71], v[150:153], v[198:201], v[68:71]
	v_mfma_f32_16x16x32_bf16 v[64:67], v[164:167], v[198:201], v[64:67]
	v_mfma_f32_16x16x32_bf16 v[104:107], v[160:163], v[178:181], v[104:107]
	v_mfma_f32_16x16x32_bf16 v[96:99], v[168:171], v[178:181], v[96:99]
	v_mfma_f32_16x16x32_bf16 v[88:91], v[160:163], v[186:189], v[88:91]
	v_mfma_f32_16x16x32_bf16 v[84:87], v[168:171], v[186:189], v[84:87]
	v_mfma_f32_16x16x32_bf16 v[80:83], v[160:163], v[194:197], v[80:83]
	v_mfma_f32_16x16x32_bf16 v[76:79], v[168:171], v[194:197], v[76:79]
	v_mfma_f32_16x16x32_bf16 v[68:71], v[160:163], v[202:205], v[68:71]
	v_mfma_f32_16x16x32_bf16 v[64:67], v[168:171], v[202:205], v[64:67]
	s_setprio 0
	s_barrier
	s_add_i32 s18, s88, s27
	v_lshl_add_u64 v[154:155], v[154:155], 0, s[40:41]
	s_mov_b32 m0, s18
	ds_read_b128 v[172:175], v159 offset:49152
	ds_read_b128 v[178:181], v159 offset:50176
	ds_read_b128 v[182:185], v159 offset:51200
	ds_read_b128 v[186:189], v159 offset:52224
	ds_read_b128 v[190:193], v159 offset:53248
	ds_read_b128 v[194:197], v159 offset:54272
	ds_read_b128 v[198:201], v159 offset:55296
	ds_read_b128 v[202:205], v159 offset:56320
	global_load_lds_dwordx4 v[154:155], off
	s_add_i32 m0, s18, 0x2000
	s_add_u32 s18, s22, 0x160080
	v_lshl_add_u64 v[154:155], v[206:207], 0, s[40:41]
	s_addc_u32 s19, s23, 0
	s_add_i32 s22, s89, s27
	global_load_lds_dwordx4 v[154:155], off
	v_lshl_add_u64 v[154:155], s[18:19], 0, v[176:177]
	s_mov_b32 m0, s22
	s_nop 0
	global_load_lds_dwordx4 v[154:155], off
	v_lshl_add_u64 v[154:155], s[18:19], 0, v[144:145]
	s_add_i32 m0, s22, 0x2000
	s_nop 0
	global_load_lds_dwordx4 v[154:155], off
	v_lshl_add_u64 v[154:155], v[208:209], 0, s[40:41]
	s_mov_b32 m0, s37
	s_nop 0
	global_load_lds_dwordx4 v[154:155], off
	v_lshl_add_u64 v[154:155], v[210:211], 0, s[40:41]
	s_mov_b32 m0, s46
	s_nop 0
	global_load_lds_dwordx4 v[154:155], off
	s_waitcnt vmcnt(8)
	s_waitcnt lgkmcnt(0)
	s_barrier
	s_setprio 1
	s_waitcnt lgkmcnt(0)
	v_mfma_f32_16x16x32_bf16 v[60:63], v[128:131], v[172:175], v[60:63]
	v_mfma_f32_16x16x32_bf16 v[56:59], v[136:139], v[172:175], v[56:59]
	v_mfma_f32_16x16x32_bf16 v[52:55], v[128:131], v[182:185], v[52:55]
	v_mfma_f32_16x16x32_bf16 v[48:51], v[136:139], v[182:185], v[48:51]
	v_mfma_f32_16x16x32_bf16 v[44:47], v[128:131], v[190:193], v[44:47]
	v_mfma_f32_16x16x32_bf16 v[32:35], v[136:139], v[190:193], v[32:35]
	v_mfma_f32_16x16x32_bf16 v[16:19], v[128:131], v[198:201], v[16:19]
	v_mfma_f32_16x16x32_bf16 v[8:11], v[136:139], v[198:201], v[8:11]
	v_mfma_f32_16x16x32_bf16 v[60:63], v[132:135], v[178:181], v[60:63]
	v_mfma_f32_16x16x32_bf16 v[56:59], v[140:143], v[178:181], v[56:59]
	v_mfma_f32_16x16x32_bf16 v[52:55], v[132:135], v[186:189], v[52:55]
	v_mfma_f32_16x16x32_bf16 v[48:51], v[140:143], v[186:189], v[48:51]
	v_mfma_f32_16x16x32_bf16 v[44:47], v[132:135], v[194:197], v[44:47]
	v_mfma_f32_16x16x32_bf16 v[32:35], v[140:143], v[194:197], v[32:35]
	v_mfma_f32_16x16x32_bf16 v[16:19], v[132:135], v[202:205], v[16:19]
	v_mfma_f32_16x16x32_bf16 v[8:11], v[140:143], v[202:205], v[8:11]
	v_mfma_f32_16x16x32_bf16 v[40:43], v[150:153], v[172:175], v[40:43]
	v_mfma_f32_16x16x32_bf16 v[36:39], v[164:167], v[172:175], v[36:39]
	v_mfma_f32_16x16x32_bf16 v[28:31], v[150:153], v[182:185], v[28:31]
	v_mfma_f32_16x16x32_bf16 v[24:27], v[164:167], v[182:185], v[24:27]
	v_mfma_f32_16x16x32_bf16 v[20:23], v[150:153], v[190:193], v[20:23]
	v_mfma_f32_16x16x32_bf16 v[12:15], v[164:167], v[190:193], v[12:15]
	v_mfma_f32_16x16x32_bf16 v[4:7], v[150:153], v[198:201], v[4:7]
	v_mfma_f32_16x16x32_bf16 v[0:3], v[164:167], v[198:201], v[0:3]
	v_mfma_f32_16x16x32_bf16 v[40:43], v[160:163], v[178:181], v[40:43]
	v_mfma_f32_16x16x32_bf16 v[36:39], v[168:171], v[178:181], v[36:39]
	v_mfma_f32_16x16x32_bf16 v[28:31], v[160:163], v[186:189], v[28:31]
	v_mfma_f32_16x16x32_bf16 v[24:27], v[168:171], v[186:189], v[24:27]
	v_mfma_f32_16x16x32_bf16 v[20:23], v[160:163], v[194:197], v[20:23]
	v_mfma_f32_16x16x32_bf16 v[12:15], v[168:171], v[194:197], v[12:15]
	v_mfma_f32_16x16x32_bf16 v[4:7], v[160:163], v[202:205], v[4:7]
	v_mfma_f32_16x16x32_bf16 v[0:3], v[168:171], v[202:205], v[0:3]
	s_setprio 0
	s_barrier
	s_add_u32 s49, s49, 0x100
	s_addc_u32 s96, s96, 0
	s_cmp_ge_u32 s97, s72
	s_mov_b64 s[18:19], s[20:21]
	s_mov_b32 s22, s97
	s_cbranch_scc0 .LBB0_1801
	s_and_b64 vcc, exec, s[10:11]
	s_cbranch_vccz .LBB0_1804
	s_barrier
